# causal attention: waves skip key tiles that lie entirely after their 32 query rows (restores the SGPRs the skipped code would have restored)
# speedup vs baseline: 1.0043x; 1.0017x over previous
.LBB0_734:
	s_add_i32 s0, s82, 32
	s_cmp_ge_i32 s84, s0
	s_cbranch_scc1 .Lattn_skip1
	ds_read_b128 v[194:197], v139 offset:32768
	ds_read_b128 v[226:229], v139 offset:45056
	ds_read_b128 v[234:237], v202 offset:32768
	ds_read_b128 v[230:233], v220
	ds_read_b128 v[238:241], v220 offset:1024
	s_add_i32 s0, s84, 63
	s_cmp_le_i32 s0, s82
	s_waitcnt lgkmcnt(4)
	v_mfma_f32_32x32x16_bf16 v[82:97], v[194:197], v[98:101], 0
	ds_read_b128 v[194:197], v202 offset:45056
	s_waitcnt lgkmcnt(4)
	v_mfma_f32_32x32x16_bf16 v[66:81], v[226:229], v[98:101], 0
	ds_read_b128 v[226:229], v203 offset:32768
	s_waitcnt lgkmcnt(4)
	v_mfma_f32_32x32x16_bf16 v[82:97], v[234:237], v[102:105], v[82:97]
	ds_read_b128 v[234:237], v203 offset:45056
	s_waitcnt lgkmcnt(2)
	v_mfma_f32_32x32x16_bf16 v[66:81], v[194:197], v[102:105], v[66:81]
	ds_read_b128 v[194:197], v204 offset:32768
	s_waitcnt lgkmcnt(2)
	v_mfma_f32_32x32x16_bf16 v[82:97], v[226:229], v[106:109], v[82:97]
	ds_read_b128 v[226:229], v204 offset:45056
	s_waitcnt lgkmcnt(2)
	v_mfma_f32_32x32x16_bf16 v[66:81], v[234:237], v[106:109], v[66:81]
	ds_read_b128 v[234:237], v139 offset:32896
	s_waitcnt lgkmcnt(2)
	v_mfma_f32_32x32x16_bf16 v[82:97], v[194:197], v[110:113], v[82:97]
	ds_read_b128 v[194:197], v139 offset:45184
	s_waitcnt lgkmcnt(2)
	v_mfma_f32_32x32x16_bf16 v[66:81], v[226:229], v[110:113], v[66:81]
	ds_read_b128 v[226:229], v202 offset:32896
	s_waitcnt lgkmcnt(2)
	v_mfma_f32_32x32x16_bf16 v[82:97], v[234:237], v[230:233], v[82:97]
	ds_read_b128 v[234:237], v202 offset:45184
	s_waitcnt lgkmcnt(2)
	v_mfma_f32_32x32x16_bf16 v[66:81], v[194:197], v[230:233], v[66:81]
	ds_read_b128 v[194:197], v203 offset:32896
	ds_read_b128 v[230:233], v220 offset:2048
	s_waitcnt lgkmcnt(3)
	v_mfma_f32_32x32x16_bf16 v[82:97], v[226:229], v[238:241], v[82:97]
	ds_read_b128 v[226:229], v203 offset:45184
	s_waitcnt lgkmcnt(3)
	v_mfma_f32_32x32x16_bf16 v[66:81], v[234:237], v[238:241], v[66:81]
	ds_read_b128 v[234:237], v204 offset:32896
	ds_read_b128 v[238:241], v220 offset:3072
	s_waitcnt lgkmcnt(3)
	v_mfma_f32_32x32x16_bf16 v[82:97], v[194:197], v[230:233], v[82:97]
	ds_read_b128 v[194:197], v204 offset:45184
	s_waitcnt lgkmcnt(3)
	v_mfma_f32_32x32x16_bf16 v[66:81], v[226:229], v[230:233], v[66:81]
	ds_read_b128 v[226:229], v139 offset:33024
	ds_read_b128 v[230:233], v220 offset:4096
	s_waitcnt lgkmcnt(3)
	v_mfma_f32_32x32x16_bf16 v[82:97], v[234:237], v[238:241], v[82:97]
	ds_read_b128 v[234:237], v139 offset:45312
	s_waitcnt lgkmcnt(3)
	v_mfma_f32_32x32x16_bf16 v[66:81], v[194:197], v[238:241], v[66:81]
	ds_read_b128 v[194:197], v202 offset:33024
	ds_read_b128 v[238:241], v220 offset:5120
	s_waitcnt lgkmcnt(3)
	v_mfma_f32_32x32x16_bf16 v[82:97], v[226:229], v[230:233], v[82:97]
	ds_read_b128 v[226:229], v202 offset:45312
	s_waitcnt lgkmcnt(3)
	v_mfma_f32_32x32x16_bf16 v[66:81], v[234:237], v[230:233], v[66:81]
	ds_read_b128 v[234:237], v203 offset:33024
	ds_read_b128 v[230:233], v220 offset:6144
	s_waitcnt lgkmcnt(3)
	v_mfma_f32_32x32x16_bf16 v[82:97], v[194:197], v[238:241], v[82:97]
	ds_read_b128 v[194:197], v203 offset:45312
	s_waitcnt lgkmcnt(3)
	v_mfma_f32_32x32x16_bf16 v[66:81], v[226:229], v[238:241], v[66:81]
	ds_read_b128 v[226:229], v204 offset:33024
	ds_read_b128 v[238:241], v220 offset:7168
	s_waitcnt lgkmcnt(3)
	v_mfma_f32_32x32x16_bf16 v[82:97], v[234:237], v[230:233], v[82:97]
	ds_read_b128 v[234:237], v204 offset:45312
	s_waitcnt lgkmcnt(3)
	v_mfma_f32_32x32x16_bf16 v[66:81], v[194:197], v[230:233], v[66:81]
	s_waitcnt lgkmcnt(1)
	v_mfma_f32_32x32x16_bf16 v[82:97], v[226:229], v[238:241], v[82:97]
	s_waitcnt lgkmcnt(0)
	v_mfma_f32_32x32x16_bf16 v[66:81], v[234:237], v[238:241], v[66:81]
	s_nop 1
	s_cbranch_scc1 .LBB0_736
	v_cmp_gt_i32_e64 s[70:71], 26, v221
	v_cmp_gt_i32_e64 s[72:73], 27, v221
	v_cmp_gt_i32_e64 s[68:69], 25, v221
	s_and_b64 s[70:71], s[72:73], s[70:71]
	v_cmp_gt_i32_e64 s[66:67], 24, v221
	s_and_b64 s[68:69], s[70:71], s[68:69]
	v_cmp_gt_i32_e64 s[64:65], 19, v221
	s_and_b64 s[66:67], s[68:69], s[66:67]
	v_cmp_gt_i32_e64 s[62:63], 18, v221
	s_and_b64 s[64:65], s[66:67], s[64:65]
	v_cmp_gt_i32_e64 s[56:57], 17, v221
	s_and_b64 s[62:63], s[64:65], s[62:63]
	v_cmp_gt_i32_e64 s[54:55], 16, v221
	s_and_b64 s[56:57], s[62:63], s[56:57]
	v_cmp_gt_i32_e64 s[52:53], 11, v221
	s_and_b64 s[54:55], s[56:57], s[54:55]
	v_cmp_gt_i32_e64 s[50:51], 10, v221
	s_and_b64 s[52:53], s[54:55], s[52:53]
	v_cmp_gt_i32_e64 s[48:49], 9, v221
	s_and_b64 s[50:51], s[52:53], s[50:51]
	v_cmp_gt_i32_e64 s[46:47], 8, v221
	s_and_b64 s[48:49], s[50:51], s[48:49]
	v_cmp_gt_i32_e64 s[44:45], 3, v221
	s_and_b64 s[46:47], s[48:49], s[46:47]
	v_cmp_gt_i32_e64 s[42:43], 2, v221
	s_and_b64 s[44:45], s[46:47], s[44:45]
	v_cmp_gt_i32_e64 s[40:41], 1, v221
	s_and_b64 s[42:43], s[44:45], s[42:43]
	v_cmp_gt_i32_e64 s[38:39], 0, v221
	s_and_b64 s[40:41], s[42:43], s[40:41]
	s_and_b64 s[38:39], s[40:41], s[38:39]
	v_cmp_gt_i32_e64 s[36:37], 58, v221
	v_cndmask_b32_e64 v82, v82, v216, s[38:39]
	v_cmp_gt_i32_e64 s[38:39], 59, v221
	v_cmp_gt_i32_e64 s[34:35], 57, v221
	s_and_b64 s[36:37], s[38:39], s[36:37]
	v_cmp_gt_i32_e64 s[0:1], 56, v221
	s_and_b64 s[34:35], s[36:37], s[34:35]
	v_cmp_gt_i32_e64 s[30:31], 51, v221
	s_and_b64 s[0:1], s[34:35], s[0:1]
	v_cmp_gt_i32_e64 s[28:29], 50, v221
	v_cndmask_b32_e64 v78, v78, v216, s[0:1]
	s_and_b64 s[0:1], s[0:1], s[30:31]
	v_cmp_gt_i32_e64 s[26:27], 49, v221
	v_cndmask_b32_e64 v77, v77, v216, s[0:1]
	s_and_b64 s[0:1], s[0:1], s[28:29]
	v_cmp_gt_i32_e64 s[24:25], 48, v221
	v_cndmask_b32_e64 v76, v76, v216, s[0:1]
	s_and_b64 s[0:1], s[0:1], s[26:27]
	v_cmp_gt_i32_e64 s[22:23], 43, v221
	v_cndmask_b32_e64 v75, v75, v216, s[0:1]
	s_and_b64 s[0:1], s[0:1], s[24:25]
	v_cmp_gt_i32_e64 s[20:21], 42, v221
	v_cndmask_b32_e64 v74, v74, v216, s[0:1]
	s_and_b64 s[0:1], s[0:1], s[22:23]
	v_cmp_gt_i32_e64 s[18:19], 41, v221
	v_cndmask_b32_e64 v73, v73, v216, s[0:1]
	s_and_b64 s[0:1], s[0:1], s[20:21]
	v_cmp_gt_i32_e64 s[16:17], 40, v221
	v_cndmask_b32_e64 v72, v72, v216, s[0:1]
	s_and_b64 s[0:1], s[0:1], s[18:19]
	v_cmp_gt_i32_e64 s[14:15], 35, v221
	v_cndmask_b32_e64 v71, v71, v216, s[0:1]
	s_and_b64 s[0:1], s[0:1], s[16:17]
	v_cmp_gt_i32_e64 s[12:13], 34, v221
	v_cndmask_b32_e64 v70, v70, v216, s[0:1]
	s_and_b64 s[0:1], s[0:1], s[14:15]
	v_cmp_gt_i32_e64 s[10:11], 33, v221
	v_cndmask_b32_e64 v69, v69, v216, s[0:1]
	s_and_b64 s[0:1], s[0:1], s[12:13]
	v_cmp_gt_i32_e32 vcc, 32, v221
	v_cndmask_b32_e64 v68, v68, v216, s[0:1]
	s_and_b64 s[0:1], s[0:1], s[10:11]
	s_and_b64 vcc, s[0:1], vcc
	v_cndmask_b32_e64 v97, v97, v216, s[72:73]
	v_cndmask_b32_e64 v96, v96, v216, s[70:71]
	v_cndmask_b32_e64 v95, v95, v216, s[68:69]
	v_cndmask_b32_e64 v94, v94, v216, s[66:67]
	v_cndmask_b32_e64 v93, v93, v216, s[64:65]
	v_cndmask_b32_e64 v92, v92, v216, s[62:63]
	v_cndmask_b32_e64 v91, v91, v216, s[56:57]
	v_cndmask_b32_e64 v90, v90, v216, s[54:55]
	v_cndmask_b32_e64 v89, v89, v216, s[52:53]
	v_cndmask_b32_e64 v88, v88, v216, s[50:51]
	v_cndmask_b32_e64 v87, v87, v216, s[48:49]
	v_cndmask_b32_e64 v86, v86, v216, s[46:47]
	v_cndmask_b32_e64 v85, v85, v216, s[44:45]
	v_cndmask_b32_e64 v84, v84, v216, s[42:43]
	v_cndmask_b32_e64 v83, v83, v216, s[40:41]
	v_cndmask_b32_e64 v81, v81, v216, s[38:39]
	v_cndmask_b32_e64 v80, v80, v216, s[36:37]
	v_cndmask_b32_e64 v79, v79, v216, s[34:35]
	v_cndmask_b32_e64 v67, v67, v216, s[0:1]
	v_cndmask_b32_e32 v66, v66, v216, vcc

.Lattn_stage1:
	s_waitcnt vmcnt(0)
	s_waitcnt vmcnt(2)
	ds_write_b128 v211, v[122:125] offset:57344
	s_waitcnt vmcnt(1)
	ds_write_b128 v212, v[126:129] offset:57344
	s_waitcnt vmcnt(0)
	ds_write_b128 v213, v[130:133] offset:57344
	ds_write_b128 v214, v[114:117] offset:16384
	ds_write_b128 v215, v[118:121] offset:16384

.LBB0_744:
	s_add_i32 s0, s84, 32
	s_cmp_ge_i32 s0, s82
	s_cbranch_scc1 .Lattn_skip2
	ds_read_b128 v[194:197], v139 offset:57344
	ds_read_b128 v[226:229], v205 offset:12288
	ds_read_b128 v[234:237], v202 offset:57344
	ds_read_b128 v[230:233], v220
	ds_read_b128 v[238:241], v220 offset:1024
	s_add_i32 s0, s84, 0x7f
	s_cmp_le_i32 s0, s82
	s_waitcnt lgkmcnt(4)
	v_mfma_f32_32x32x16_bf16 v[82:97], v[194:197], v[98:101], 0
	ds_read_b128 v[194:197], v206 offset:12288
	s_waitcnt lgkmcnt(4)
	v_mfma_f32_32x32x16_bf16 v[66:81], v[226:229], v[98:101], 0
	ds_read_b128 v[226:229], v203 offset:57344
	s_waitcnt lgkmcnt(4)
	v_mfma_f32_32x32x16_bf16 v[82:97], v[234:237], v[102:105], v[82:97]
	ds_read_b128 v[234:237], v207 offset:12288
	s_waitcnt lgkmcnt(2)
	v_mfma_f32_32x32x16_bf16 v[66:81], v[194:197], v[102:105], v[66:81]
	ds_read_b128 v[194:197], v204 offset:57344
	s_waitcnt lgkmcnt(2)
	v_mfma_f32_32x32x16_bf16 v[82:97], v[226:229], v[106:109], v[82:97]
	ds_read_b128 v[226:229], v208 offset:12288
	s_waitcnt lgkmcnt(2)
	v_mfma_f32_32x32x16_bf16 v[66:81], v[234:237], v[106:109], v[66:81]
	ds_read_b128 v[234:237], v139 offset:57472
	s_waitcnt lgkmcnt(2)
	v_mfma_f32_32x32x16_bf16 v[82:97], v[194:197], v[110:113], v[82:97]
	ds_read_b128 v[194:197], v205 offset:12416
	s_waitcnt lgkmcnt(2)
	v_mfma_f32_32x32x16_bf16 v[66:81], v[226:229], v[110:113], v[66:81]
	ds_read_b128 v[226:229], v202 offset:57472
	s_waitcnt lgkmcnt(2)
	v_mfma_f32_32x32x16_bf16 v[82:97], v[234:237], v[230:233], v[82:97]
	ds_read_b128 v[234:237], v206 offset:12416
	s_waitcnt lgkmcnt(2)
	v_mfma_f32_32x32x16_bf16 v[66:81], v[194:197], v[230:233], v[66:81]
	ds_read_b128 v[194:197], v203 offset:57472
	ds_read_b128 v[230:233], v220 offset:2048
	s_waitcnt lgkmcnt(3)
	v_mfma_f32_32x32x16_bf16 v[82:97], v[226:229], v[238:241], v[82:97]
	ds_read_b128 v[226:229], v207 offset:12416
	s_waitcnt lgkmcnt(3)
	v_mfma_f32_32x32x16_bf16 v[66:81], v[234:237], v[238:241], v[66:81]
	ds_read_b128 v[234:237], v204 offset:57472
	ds_read_b128 v[238:241], v220 offset:3072
	s_waitcnt lgkmcnt(3)
	v_mfma_f32_32x32x16_bf16 v[82:97], v[194:197], v[230:233], v[82:97]
	ds_read_b128 v[194:197], v208 offset:12416
	s_waitcnt lgkmcnt(3)
	v_mfma_f32_32x32x16_bf16 v[66:81], v[226:229], v[230:233], v[66:81]
	ds_read_b128 v[226:229], v139 offset:57600
	ds_read_b128 v[230:233], v220 offset:4096
	s_waitcnt lgkmcnt(3)
	v_mfma_f32_32x32x16_bf16 v[82:97], v[234:237], v[238:241], v[82:97]
	ds_read_b128 v[234:237], v205 offset:12544
	s_waitcnt lgkmcnt(3)
	v_mfma_f32_32x32x16_bf16 v[66:81], v[194:197], v[238:241], v[66:81]
	ds_read_b128 v[194:197], v202 offset:57600
	ds_read_b128 v[238:241], v220 offset:5120
	s_waitcnt lgkmcnt(3)
	v_mfma_f32_32x32x16_bf16 v[82:97], v[226:229], v[230:233], v[82:97]
	ds_read_b128 v[226:229], v206 offset:12544
	s_waitcnt lgkmcnt(3)
	v_mfma_f32_32x32x16_bf16 v[66:81], v[234:237], v[230:233], v[66:81]
	ds_read_b128 v[234:237], v203 offset:57600
	ds_read_b128 v[230:233], v220 offset:6144
	s_waitcnt lgkmcnt(3)
	v_mfma_f32_32x32x16_bf16 v[82:97], v[194:197], v[238:241], v[82:97]
	ds_read_b128 v[194:197], v207 offset:12544
	s_waitcnt lgkmcnt(3)
	v_mfma_f32_32x32x16_bf16 v[66:81], v[226:229], v[238:241], v[66:81]
	ds_read_b128 v[226:229], v204 offset:57600
	ds_read_b128 v[238:241], v220 offset:7168
	s_waitcnt lgkmcnt(3)
	v_mfma_f32_32x32x16_bf16 v[82:97], v[234:237], v[230:233], v[82:97]
	ds_read_b128 v[234:237], v208 offset:12544
	s_waitcnt lgkmcnt(3)
	v_mfma_f32_32x32x16_bf16 v[66:81], v[194:197], v[230:233], v[66:81]
	s_waitcnt lgkmcnt(1)
	v_mfma_f32_32x32x16_bf16 v[82:97], v[226:229], v[238:241], v[82:97]
	s_waitcnt lgkmcnt(0)
	v_mfma_f32_32x32x16_bf16 v[66:81], v[234:237], v[238:241], v[66:81]
	s_nop 1
	s_cbranch_scc1 .LBB0_746
	v_subrev_u32_e32 v194, 64, v221
	v_cmp_gt_i32_e64 s[70:71], 26, v194
	v_cmp_gt_i32_e64 s[72:73], 27, v194
	v_cmp_gt_i32_e64 s[68:69], 25, v194
	s_and_b64 s[70:71], s[72:73], s[70:71]
	v_cmp_gt_i32_e64 s[66:67], 24, v194
	s_and_b64 s[68:69], s[70:71], s[68:69]
	v_cmp_gt_i32_e64 s[64:65], 19, v194
	s_and_b64 s[66:67], s[68:69], s[66:67]
	v_cmp_gt_i32_e64 s[62:63], 18, v194
	s_and_b64 s[64:65], s[66:67], s[64:65]
	v_cmp_gt_i32_e64 s[56:57], 17, v194
	s_and_b64 s[62:63], s[64:65], s[62:63]
	v_cmp_gt_i32_e64 s[54:55], 16, v194
	s_and_b64 s[56:57], s[62:63], s[56:57]
	v_cmp_gt_i32_e64 s[52:53], 11, v194
	s_and_b64 s[54:55], s[56:57], s[54:55]
	v_cmp_gt_i32_e64 s[50:51], 10, v194
	s_and_b64 s[52:53], s[54:55], s[52:53]
	v_cmp_gt_i32_e64 s[48:49], 9, v194
	s_and_b64 s[50:51], s[52:53], s[50:51]
	v_cmp_gt_i32_e64 s[46:47], 8, v194
	s_and_b64 s[48:49], s[50:51], s[48:49]
	v_cmp_gt_i32_e64 s[44:45], 3, v194
	s_and_b64 s[46:47], s[48:49], s[46:47]
	v_cmp_gt_i32_e64 s[42:43], 2, v194
	s_and_b64 s[44:45], s[46:47], s[44:45]
	v_cmp_gt_i32_e64 s[40:41], 1, v194
	s_and_b64 s[42:43], s[44:45], s[42:43]
	v_cmp_gt_i32_e64 s[38:39], 0, v194
	s_and_b64 s[40:41], s[42:43], s[40:41]
	s_and_b64 s[38:39], s[40:41], s[38:39]
	v_cmp_gt_i32_e64 s[36:37], 58, v194
	v_cndmask_b32_e64 v82, v82, v216, s[38:39]
	v_cmp_gt_i32_e64 s[38:39], 59, v194
	v_cmp_gt_i32_e64 s[34:35], 57, v194
	s_and_b64 s[36:37], s[38:39], s[36:37]
	v_cmp_gt_i32_e64 s[0:1], 56, v194
	s_and_b64 s[34:35], s[36:37], s[34:35]
	v_cmp_gt_i32_e64 s[30:31], 51, v194
	s_and_b64 s[0:1], s[34:35], s[0:1]
	v_cmp_gt_i32_e64 s[28:29], 50, v194
	v_cndmask_b32_e64 v78, v78, v216, s[0:1]
	s_and_b64 s[0:1], s[0:1], s[30:31]
	v_cmp_gt_i32_e64 s[26:27], 49, v194
	v_cndmask_b32_e64 v77, v77, v216, s[0:1]
	s_and_b64 s[0:1], s[0:1], s[28:29]
	v_cmp_gt_i32_e64 s[24:25], 48, v194
	v_cndmask_b32_e64 v76, v76, v216, s[0:1]
	s_and_b64 s[0:1], s[0:1], s[26:27]
	v_cmp_gt_i32_e64 s[22:23], 43, v194
	v_cndmask_b32_e64 v75, v75, v216, s[0:1]
	s_and_b64 s[0:1], s[0:1], s[24:25]
	v_cmp_gt_i32_e64 s[20:21], 42, v194
	v_cndmask_b32_e64 v74, v74, v216, s[0:1]
	s_and_b64 s[0:1], s[0:1], s[22:23]
	v_cmp_gt_i32_e64 s[18:19], 41, v194
	v_cndmask_b32_e64 v73, v73, v216, s[0:1]
	s_and_b64 s[0:1], s[0:1], s[20:21]
	v_cmp_gt_i32_e64 s[16:17], 40, v194
	v_cndmask_b32_e64 v72, v72, v216, s[0:1]
	s_and_b64 s[0:1], s[0:1], s[18:19]
	v_cmp_gt_i32_e64 s[14:15], 35, v194
	v_cndmask_b32_e64 v71, v71, v216, s[0:1]
	s_and_b64 s[0:1], s[0:1], s[16:17]
	v_cmp_gt_i32_e64 s[12:13], 34, v194
	v_cndmask_b32_e64 v70, v70, v216, s[0:1]
	s_and_b64 s[0:1], s[0:1], s[14:15]
	v_cmp_gt_i32_e64 s[10:11], 33, v194
	v_cndmask_b32_e64 v69, v69, v216, s[0:1]
	s_and_b64 s[0:1], s[0:1], s[12:13]
	v_cmp_gt_i32_e32 vcc, 32, v194
	v_cndmask_b32_e64 v68, v68, v216, s[0:1]
	s_and_b64 s[0:1], s[0:1], s[10:11]
	s_and_b64 vcc, s[0:1], vcc
	v_cndmask_b32_e64 v97, v97, v216, s[72:73]
	v_cndmask_b32_e64 v96, v96, v216, s[70:71]
	v_cndmask_b32_e64 v95, v95, v216, s[68:69]
	v_cndmask_b32_e64 v94, v94, v216, s[66:67]
	v_cndmask_b32_e64 v93, v93, v216, s[64:65]
	v_cndmask_b32_e64 v92, v92, v216, s[62:63]
	v_cndmask_b32_e64 v91, v91, v216, s[56:57]
	v_cndmask_b32_e64 v90, v90, v216, s[54:55]
	v_cndmask_b32_e64 v89, v89, v216, s[52:53]
	v_cndmask_b32_e64 v88, v88, v216, s[50:51]
	v_cndmask_b32_e64 v87, v87, v216, s[48:49]
	v_cndmask_b32_e64 v86, v86, v216, s[46:47]
	v_cndmask_b32_e64 v85, v85, v216, s[44:45]
	v_cndmask_b32_e64 v84, v84, v216, s[42:43]
	v_cndmask_b32_e64 v83, v83, v216, s[40:41]
	v_cndmask_b32_e64 v81, v81, v216, s[38:39]
	v_cndmask_b32_e64 v80, v80, v216, s[36:37]
	v_cndmask_b32_e64 v79, v79, v216, s[34:35]
	v_cndmask_b32_e64 v67, v67, v216, s[0:1]
	v_cndmask_b32_e32 v66, v66, v216, vcc

.Lattn_stage2:
	s_waitcnt vmcnt(0)
	s_waitcnt vmcnt(2)
	ds_write_b128 v211, v[122:125] offset:32768
	s_waitcnt vmcnt(1)
	ds_write_b128 v212, v[126:129] offset:32768
	s_waitcnt vmcnt(0)
	ds_write_b128 v213, v[130:133] offset:32768
	ds_write_b128 v214, v[114:117]
	ds_write_b128 v215, v[118:121]
	s_branch .LBB0_731
.Lattn_skip1:
	v_mov_b32_e32 v0, 1.0
	v_mov_b32_e32 v222, 0
	v_mov_b32_e32 v223, 0
	s_andn2_b64 vcc, exec, s[4:5]
	s_cbranch_vccnz .LBB0_742
	s_branch .Lattn_stage1
.Lattn_skip2:
	v_mov_b32_e32 v194, 1.0
	v_mov_b32_e32 v66, 0
	v_mov_b32_e32 v67, 0
	s_mov_b32 s70, s80
	s_mov_b32 s71, s81
	s_mov_b64 s[72:73], s[86:87]
	s_andn2_b64 vcc, exec, s[94:95]
	s_cbranch_vccnz .LBB0_731
	s_branch .Lattn_stage2
